# rg output tile: during its last stage each block touches the input rows of its next rg tile (one cache line per thread)
# speedup vs baseline: 1.1033x; 1.0039x over previous
; __device__ __forceinline__ float bf2f(bf16_t h) { return __uint_as_float(((unsigned)h) << 16); }
; __device__ void rg_tile(unsigned char* lds, const Params& p, int l, int b, int ck, int hh, bool outmode) {
;     ...
;       car_pre = car[((size_t)(b * 36 + ck) * 2 + d_) * 256 + hh * 64 + j_];
; #pragma unroll
;       for (int q = 0; q < 8; ++q) gp_pre[q] = bf2f(z[(size_t)(rowbase + t0 + w * 8 + q) * ZS + 2816 + 256 + hh * 64 + lane]);
;     } else {
; #pragma unroll
;       for (int q = 0; q < 8; ++q) gp_pre[q] = 0.f;
;     }
;   }
;   const int chm_ = hh * 64 + (w & 3) * 16 + lr, dm_ = w >> 2;
;   const float br = p.in[22][(size_t)l * 1024 + (dm_ * 2 + 0) * 256 + chm_];
;   const float bi = p.in[22][(size_t)l * 1024 + (dm_ * 2 + 1) * 256 + chm_];
;   const float lam_ = p.in[23][(size_t)l * 512 + dm_ * 256 + chm_];
;   {
;     const int i = tid & 63, tq = tid >> 6;
;     const int ch = hh * 64 + i;
;     const float* wc = p.in[20] + (size_t)l * 4 * 256 + ch;
;     const float w0 = wc[0], w1 = wc[256], w2 = wc[512], w3 = wc[768];
; #pragma unroll
;     for (int ii = 0; ii < 8; ++ii) {
;       const int tt = tq * 8 + ii;
;       const int tp = t0 + tt;
;       const int tm1 = tp - 1 >= 0 ? tp - 1 : 0, tp1 = tp + 1 < L ? tp + 1 : L - 1, tp2 = tp + 2 < L ? tp + 2 : L - 1;
;       const float z0 = bf2f(z[(size_t)(rowbase + tm1) * ZS + 2816 + ch]);
;       const float z1 = bf2f(z[(size_t)(rowbase + tp) * ZS + 2816 + ch]);
;       const float z2 = bf2f(z[(size_t)(rowbase + tp1) * ZS + 2816 + ch]);
;       const float z3 = bf2f(z[(size_t)(rowbase + tp2) * ZS + 2816 + ch]);
; __global__ void __launch_bounds__(512) fwd_kernel(Params p) {
;     ...
;         } else if (item < n_ml + n_rg) {
;           const int tile = item - n_ml;
;           const int hh = tile & 3, ck = cfirst + (tile >> 2) % ccnt, b = tile / (4 * ccnt);
;           rg_tile(lds, p, l, b, ck, hh, true);
.Lrgs_p5_j2:
	s_waitcnt lgkmcnt(0)
	s_barrier
	s_add_i32 s52, s13, s90
	v_readlane_b32 s53, v254, 23
	s_nop 0
	s_cmp_ge_i32 s52, s53
	s_cbranch_scc1 .Lrgpf_skip
	s_sub_i32 s52, s52, s30
	s_and_b32 s54, s52, 3
	s_lshr_b32 s55, s52, 2
	v_readlane_b32 s56, v254, 14
	v_readlane_b32 s57, v254, 11
	s_nop 0
	s_mul_hi_u32 s56, s55, s56
	s_mul_i32 s56, s56, s57
	s_sub_i32 s55, s55, s56
	s_sub_i32 s56, s55, s57
	s_cmp_ge_u32 s55, s57
	s_cselect_b32 s55, s56, s55
	s_sub_i32 s56, s55, s57
	s_cmp_ge_u32 s55, s57
	s_cselect_b32 s55, s56, s55
	v_readlane_b32 s56, v254, 22
	v_readlane_b32 s57, v254, 15
	v_readlane_b32 s59, v254, 16
	s_nop 0
	s_add_i32 s55, s55, s56
	s_mul_hi_u32 s56, s52, s59
	s_mul_i32 s58, s56, s57
	s_sub_i32 s58, s52, s58
	s_add_i32 s59, s56, 1
	s_sub_i32 s60, s58, s57
	s_cmp_ge_u32 s58, s57
	s_cselect_b32 s56, s59, s56
	s_cselect_b32 s58, s60, s58
	s_add_i32 s59, s56, 1
	s_cmp_ge_u32 s58, s57
	s_cselect_b32 s56, s59, s56
	s_lshl_b32 s57, s55, 6
	s_lshl_b32 s58, s56, 8
	s_add_i32 s59, s57, 0xffffff00
	s_add_i32 s58, s58, 0x4000
	s_lshl_b32 s60, s56, 11
	s_movk_i32 s61, 0x7ff
	s_cmp_lt_i32 s55, 4
	s_cselect_b32 s61, 0xff, s61
	s_cselect_b32 s57, s57, s59
	s_cselect_b32 s58, s58, s60
	s_add_i32 s57, s57, -1
	s_lshl_b32 s54, s54, 7
	s_addk_i32 s54, 0x1600
	v_lshrrev_b32_e32 v190, 1, v195
	v_add_u32_e32 v190, s57, v190
	v_max_i32_e32 v190, 0, v190
	v_min_i32_e32 v190, s61, v190
	v_add_u32_e32 v190, s58, v190
	v_mul_u32_u24_e32 v190, 0x1a00, v190
	v_and_b32_e32 v191, 1, v195
	v_lshlrev_b32_e32 v191, 9, v191
	v_add3_u32 v190, v190, v191, s54
	v_cmp_gt_u32_e32 vcc, 0x88, v195
	s_and_saveexec_b64 s[52:53], vcc
	global_load_dword v191, v190, s[88:89]
	s_mov_b64 exec, s[52:53]
; __device__ __forceinline__ bf16_t f2bf(float f) { return (bf16_t)(pack2(f, 0.f) & 0xffffu); }
; __device__ __forceinline__ float fexp(float x) { return __expf(x); }
; __device__ __forceinline__ float frcp(float x) { return __builtin_amdgcn_rcpf(x); }
; __device__ __forceinline__ float gelu_tanh(float x) {
;   const float u = 0.7978845608028654f * (x + 0.044715f * x * x * x);
;   const float th = 1.f - 2.f * frcp(fexp(2.f * u) + 1.f);
;   return 0.5f * x * (1.f + th);
; }
; __device__ void rg_tile(unsigned char* lds, const Params& p, int l, int b, int ck, int hh, bool outmode) {
;     ...
;   if (outmode) {
;     const int ch = hh * 64 + lane;
;     const float gm = p.in[24][(size_t)l * 1024 + 768 + ch];
; #pragma unroll
;     for (int q = 0; q < 8; ++q) {
;       const int tt = w * 8 + q;
;       const int row = rowbase + t0 + tt;
;       const float hr = AA[tt * 64 + lane] + AA[(64 + tt) * 64 + lane];
;       const float v = hr * gelu_tanh(gp_pre[q]);
;       const float ss = wsum(v * v, lane);
;       const float rn = rsqrtf(ss * (1.f / 64.f) + EPSF);
;       y[(size_t)row * 1024 + 768 + ch] = f2bf(v * rn * gm);
;     }
;     __syncthreads();
.Lrgpf_skip:
	s_and_b32 s0, s13, 3
	v_bfe_u32 v208, v195, 4, 2
	v_and_b32_e32 v209, 15, v195
	s_lshl_b32 s1, s44, 11
	v_lshlrev_b32_e32 v210, 8, v208
	v_lshl_add_u32 v210, v209, 4, v210
	v_add_u32_e32 v210, s1, v210
	v_add_u32_e32 v210, 0xf500, v210
	ds_read_b128 v[212:215], v210
	ds_read_b128 v[216:219], v210 offset:16384
	ds_read_b128 v[154:157], v210 offset:1024
	ds_read_b128 v[158:161], v210 offset:17408
	v_readlane_b32 s2, v251, 31
	v_readlane_b32 s3, v251, 32
	s_add_i32 s4, s48, s45
	s_lshl_b32 s4, s4, 11
	s_lshl_b32 s5, s0, 7
	s_add_i32 s4, s4, s5
	s_addk_i32 s4, 0x600
	s_add_u32 s2, s2, s4
	s_addc_u32 s3, s3, 0
	v_lshlrev_b32_e32 v211, 11, v208
	v_lshl_add_u32 v211, v209, 3, v211
	v_lshlrev_b32_e32 v162, 16, v204
	v_and_b32_e32 v163, 0xffff0000, v204
	v_lshlrev_b32_e32 v164, 16, v205
	v_and_b32_e32 v165, 0xffff0000, v205
	v_lshlrev_b32_e32 v166, 16, v206
	v_and_b32_e32 v167, 0xffff0000, v206
	v_lshlrev_b32_e32 v168, 16, v207
	v_and_b32_e32 v169, 0xffff0000, v207
	v_mul_f32_e32 v170, 0x3d372713, v162
	v_mul_f32_e32 v171, 0x3d372713, v163
	v_mul_f32_e32 v172, 0x3d372713, v164
	v_mul_f32_e32 v173, 0x3d372713, v165
	v_mul_f32_e32 v174, 0x3d372713, v166
	v_mul_f32_e32 v175, 0x3d372713, v167
	v_mul_f32_e32 v176, 0x3d372713, v168
	v_mul_f32_e32 v177, 0x3d372713, v169
	v_mul_f32_e32 v170, v170, v162
	v_mul_f32_e32 v171, v171, v163
	v_mul_f32_e32 v172, v172, v164
	v_mul_f32_e32 v173, v173, v165
	v_mul_f32_e32 v174, v174, v166
	v_mul_f32_e32 v175, v175, v167
	v_mul_f32_e32 v176, v176, v168
	v_mul_f32_e32 v177, v177, v169
	v_fma_f32 v170, v170, v162, v162
	v_fma_f32 v171, v171, v163, v163
	v_fma_f32 v172, v172, v164, v164
	v_fma_f32 v173, v173, v165, v165
	v_fma_f32 v174, v174, v166, v166
	v_fma_f32 v175, v175, v167, v167
	v_fma_f32 v176, v176, v168, v168
	v_fma_f32 v177, v177, v169, v169
	v_mul_f32_e32 v170, 0x3f4c422a, v170
	v_mul_f32_e32 v171, 0x3f4c422a, v171
	v_mul_f32_e32 v172, 0x3f4c422a, v172
	v_mul_f32_e32 v173, 0x3f4c422a, v173
	v_mul_f32_e32 v174, 0x3f4c422a, v174
	v_mul_f32_e32 v175, 0x3f4c422a, v175
	v_mul_f32_e32 v176, 0x3f4c422a, v176
	v_mul_f32_e32 v177, 0x3f4c422a, v177
	v_add_f32_e32 v170, v170, v170
	v_add_f32_e32 v171, v171, v171
	v_add_f32_e32 v172, v172, v172
	v_add_f32_e32 v173, v173, v173
	v_add_f32_e32 v174, v174, v174
	v_add_f32_e32 v175, v175, v175
	v_add_f32_e32 v176, v176, v176
	v_add_f32_e32 v177, v177, v177
	v_mul_f32_e32 v170, 0x3fb8aa3b, v170
	v_mul_f32_e32 v171, 0x3fb8aa3b, v171
	v_mul_f32_e32 v172, 0x3fb8aa3b, v172
	v_mul_f32_e32 v173, 0x3fb8aa3b, v173
	v_mul_f32_e32 v174, 0x3fb8aa3b, v174
	v_mul_f32_e32 v175, 0x3fb8aa3b, v175
	v_mul_f32_e32 v176, 0x3fb8aa3b, v176
	v_mul_f32_e32 v177, 0x3fb8aa3b, v177
	v_exp_f32_e32 v170, v170
	v_exp_f32_e32 v171, v171
	v_exp_f32_e32 v172, v172
	v_exp_f32_e32 v173, v173
	v_exp_f32_e32 v174, v174
	v_exp_f32_e32 v175, v175
	v_exp_f32_e32 v176, v176
	v_exp_f32_e32 v177, v177
	v_add_f32_e32 v170, 1.0, v170
	v_add_f32_e32 v171, 1.0, v171
	v_add_f32_e32 v172, 1.0, v172
	v_add_f32_e32 v173, 1.0, v173
	v_add_f32_e32 v174, 1.0, v174
	v_add_f32_e32 v175, 1.0, v175
	v_add_f32_e32 v176, 1.0, v176
	v_add_f32_e32 v177, 1.0, v177
	v_rcp_f32_e32 v170, v170
	v_rcp_f32_e32 v171, v171
	v_rcp_f32_e32 v172, v172
	v_rcp_f32_e32 v173, v173
	v_rcp_f32_e32 v174, v174
	v_rcp_f32_e32 v175, v175
	v_rcp_f32_e32 v176, v176
	v_rcp_f32_e32 v177, v177
	v_mul_f32_e32 v162, 0.5, v162
	v_mul_f32_e32 v163, 0.5, v163
	v_mul_f32_e32 v164, 0.5, v164
	v_mul_f32_e32 v165, 0.5, v165
	v_mul_f32_e32 v166, 0.5, v166
	v_mul_f32_e32 v167, 0.5, v167
	v_mul_f32_e32 v168, 0.5, v168
	v_mul_f32_e32 v169, 0.5, v169
	v_fma_f32 v170, v170, -2.0, 1.0
	v_fma_f32 v171, v171, -2.0, 1.0
	v_fma_f32 v172, v172, -2.0, 1.0
	v_fma_f32 v173, v173, -2.0, 1.0
	v_fma_f32 v174, v174, -2.0, 1.0
	v_fma_f32 v175, v175, -2.0, 1.0
	v_fma_f32 v176, v176, -2.0, 1.0
	v_fma_f32 v177, v177, -2.0, 1.0
	v_add_f32_e32 v170, 1.0, v170
	v_add_f32_e32 v171, 1.0, v171
	v_add_f32_e32 v172, 1.0, v172
	v_add_f32_e32 v173, 1.0, v173
	v_add_f32_e32 v174, 1.0, v174
	v_add_f32_e32 v175, 1.0, v175
	v_add_f32_e32 v176, 1.0, v176
	v_add_f32_e32 v177, 1.0, v177
	v_mul_f32_e32 v170, v162, v170
	v_mul_f32_e32 v171, v163, v171
	v_mul_f32_e32 v172, v164, v172
	v_mul_f32_e32 v173, v165, v173
	v_mul_f32_e32 v174, v166, v174
	v_mul_f32_e32 v175, v167, v175
	v_mul_f32_e32 v176, v168, v176
	v_mul_f32_e32 v177, v169, v177
	s_waitcnt lgkmcnt(0)
	v_add_f32_e32 v212, v212, v216
	v_add_f32_e32 v213, v213, v217
	v_add_f32_e32 v214, v214, v218
	v_add_f32_e32 v215, v215, v219
	v_add_f32_e32 v154, v154, v158
	v_add_f32_e32 v155, v155, v159
	v_add_f32_e32 v156, v156, v160
	v_add_f32_e32 v157, v157, v161
	v_mul_f32_e32 v178, v212, v170
	v_mul_f32_e32 v179, v213, v171
	v_mul_f32_e32 v180, v214, v172
	v_mul_f32_e32 v181, v215, v173
	v_mul_f32_e32 v182, v154, v174
	v_mul_f32_e32 v183, v155, v175
	v_mul_f32_e32 v184, v156, v176
	v_mul_f32_e32 v185, v157, v177
	v_mul_f32_e32 v186, v178, v178
	v_mul_f32_e32 v187, v182, v182
	v_fmac_f32_e32 v186, v179, v179
	v_fmac_f32_e32 v187, v183, v183
	v_fmac_f32_e32 v186, v180, v180
	v_fmac_f32_e32 v187, v184, v184
	v_fmac_f32_e32 v186, v181, v181
	v_fmac_f32_e32 v187, v185, v185
	s_nop 1
	v_add_f32_dpp v186, v186, v186 quad_perm:[1,0,3,2] row_mask:0xf bank_mask:0xf
	v_add_f32_dpp v187, v187, v187 quad_perm:[1,0,3,2] row_mask:0xf bank_mask:0xf
	s_nop 0
	v_add_f32_dpp v186, v186, v186 quad_perm:[2,3,0,1] row_mask:0xf bank_mask:0xf
	v_add_f32_dpp v187, v187, v187 quad_perm:[2,3,0,1] row_mask:0xf bank_mask:0xf
	s_nop 0
	v_add_f32_dpp v186, v186, v186 row_half_mirror row_mask:0xf bank_mask:0xf
	v_add_f32_dpp v187, v187, v187 row_half_mirror row_mask:0xf bank_mask:0xf
	s_nop 0
	v_add_f32_dpp v186, v186, v186 row_mirror row_mask:0xf bank_mask:0xf
	v_add_f32_dpp v187, v187, v187 row_mirror row_mask:0xf bank_mask:0xf
	s_nop 0
	v_fmamk_f32 v188, v186, 0x3c800000, v194
	v_fmamk_f32 v189, v187, 0x3c800000, v194
	v_rsq_f32_e32 v188, v188
	v_rsq_f32_e32 v189, v189
	s_nop 0
	v_mul_f32_e32 v178, v178, v188
	v_mul_f32_e32 v179, v179, v188
	v_mul_f32_e32 v180, v180, v188
	v_mul_f32_e32 v181, v181, v188
	v_mul_f32_e32 v182, v182, v189
	v_mul_f32_e32 v183, v183, v189
	v_mul_f32_e32 v184, v184, v189
	v_mul_f32_e32 v185, v185, v189
	v_mul_f32_e32 v178, v178, v200
	v_mul_f32_e32 v179, v179, v201
	v_mul_f32_e32 v180, v180, v202
	v_mul_f32_e32 v181, v181, v203
	v_mul_f32_e32 v182, v182, v200
	v_mul_f32_e32 v183, v183, v201
	v_mul_f32_e32 v184, v184, v202
	v_mul_f32_e32 v185, v185, v203
	v_cvt_pk_bf16_f32 v212, v178, v179
	v_cvt_pk_bf16_f32 v213, v180, v181
	v_cvt_pk_bf16_f32 v154, v182, v183
	v_cvt_pk_bf16_f32 v155, v184, v185
	global_store_dwordx2 v211, v[212:213], s[2:3]
	v_add_u32_e32 v211, 0x2000, v211
	global_store_dwordx2 v211, v[154:155], s[2:3]
	s_barrier
	s_mov_b64 s[0:1], 0
